# SGU W_s staging: 8 serialized loads issued together with counted vmcnt; squared-ReLU epilogue drops redundant canonicalizing max(x,x)
# speedup vs baseline: 1.0025x; 1.0011x over previous
; #define LAS __attribute__((address_space(3)))
; __device__ __forceinline__ unsigned cvt_pk_bf16(float lo, float hi) { unsigned r; asm volatile("v_cvt_pk_bf16_f32 %0, %1, %2" : "=v"(r) : "v"(lo), "v"(hi)); return r; }
; __device__ __forceinline__ void sgu_phase(const Params& p, LAS unsigned char* lds) {
;     ...
;         for (int i = 0; i < 8; ++i) vin[i] = *(const u32x4*)(hh + (size_t)(t0 + sb * 8 + i) * 4096 + 2048 + cg0 + cb * 8);
;         __syncthreads();
;         {
;             const int t = tid >> 2, s0 = (tid & 3) * 32;
;             const float* wrow = p.sgu_w_s + (size_t)g * 16384 + t * 128 + s0;
; #pragma unroll
;             for (int i = 0; i < 8; ++i) {
;                 const f32x4 wv = *(const f32x4*)(wrow + 4 * i);
;                 float e[4];
; #pragma unroll
;                 for (int q = 0; q < 4; ++q) { const int s = s0 + 4 * i + q; e[q] = (s <= t) ? wv[q] * rsL[s] : 0.f; }
;                 u32x2 pk; pk.x = cvt_pk_bf16(e[0], e[1]); pk.y = cvt_pk_bf16(e[2], e[3]);
;                 *(LAS u32x2*)(WsL + t * 136 + s0 + 4 * i) = pk;
.LBB0_226:
	s_or_b64 exec, exec, s[86:87]
	s_waitcnt vmcnt(2)
	v_add_u32_e32 v24, s33, v46
	v_ashrrev_i32_e32 v25, 31, v24
	s_and_b32 s86, s95, 7
	v_lshlrev_b64 v[0:1], 13, v[24:25]
	v_or_b32_e32 v2, 1, v24
	v_lshl_add_u64 v[0:1], s[76:77], 0, v[0:1]
	s_lshl_b32 s2, s86, 9
	v_ashrrev_i32_e32 v3, 31, v2
	v_lshl_add_u64 v[0:1], v[0:1], 0, s[2:3]
	v_lshlrev_b64 v[2:3], 13, v[2:3]
	v_or_b32_e32 v8, 2, v24
	v_lshl_add_u64 v[0:1], v[0:1], 0, v[168:169]
	v_lshl_add_u64 v[2:3], s[76:77], 0, v[2:3]
	v_ashrrev_i32_e32 v9, 31, v8
	v_add_co_u32_e32 v0, vcc, 0x1000, v0
	v_lshl_add_u64 v[2:3], v[2:3], 0, s[2:3]
	v_lshlrev_b64 v[8:9], 13, v[8:9]
	v_or_b32_e32 v10, 3, v24
	v_addc_co_u32_e32 v1, vcc, 0, v1, vcc
	v_lshl_add_u64 v[2:3], v[2:3], 0, v[168:169]
	v_lshl_add_u64 v[8:9], s[76:77], 0, v[8:9]
	v_ashrrev_i32_e32 v11, 31, v10
	v_add_co_u32_e32 v4, vcc, 0x1000, v2
	v_lshl_add_u64 v[8:9], v[8:9], 0, s[2:3]
	v_lshlrev_b64 v[10:11], 13, v[10:11]
	v_or_b32_e32 v16, 4, v24
	v_addc_co_u32_e32 v5, vcc, 0, v3, vcc
	v_lshl_add_u64 v[8:9], v[8:9], 0, v[168:169]
	v_lshl_add_u64 v[10:11], s[76:77], 0, v[10:11]
	v_ashrrev_i32_e32 v17, 31, v16
	v_add_co_u32_e32 v8, vcc, 0x1000, v8
	v_lshl_add_u64 v[10:11], v[10:11], 0, s[2:3]
	v_lshlrev_b64 v[16:17], 13, v[16:17]
	v_or_b32_e32 v18, 5, v24
	v_addc_co_u32_e32 v9, vcc, 0, v9, vcc
	v_lshl_add_u64 v[10:11], v[10:11], 0, v[168:169]
	v_lshl_add_u64 v[16:17], s[76:77], 0, v[16:17]
	v_ashrrev_i32_e32 v19, 31, v18
	v_add_co_u32_e32 v12, vcc, 0x1000, v10
	v_lshl_add_u64 v[16:17], v[16:17], 0, s[2:3]
	v_lshlrev_b64 v[18:19], 13, v[18:19]
	s_waitcnt vmcnt(1)
	v_or_b32_e32 v26, 6, v24
	v_addc_co_u32_e32 v13, vcc, 0, v11, vcc
	v_lshl_add_u64 v[16:17], v[16:17], 0, v[168:169]
	v_lshl_add_u64 v[18:19], s[76:77], 0, v[18:19]
	v_ashrrev_i32_e32 v27, 31, v26
	v_add_co_u32_e32 v16, vcc, 0x1000, v16
	v_lshl_add_u64 v[18:19], v[18:19], 0, s[2:3]
	v_lshlrev_b64 v[26:27], 13, v[26:27]
	v_or_b32_e32 v24, 7, v24
	v_addc_co_u32_e32 v17, vcc, 0, v17, vcc
	v_lshl_add_u64 v[18:19], v[18:19], 0, v[168:169]
	v_lshl_add_u64 v[26:27], s[76:77], 0, v[26:27]
	v_ashrrev_i32_e32 v25, 31, v24
	v_add_co_u32_e32 v20, vcc, 0x1000, v18
	v_lshl_add_u64 v[26:27], v[26:27], 0, s[2:3]
	v_lshlrev_b64 v[24:25], 13, v[24:25]
	v_addc_co_u32_e32 v21, vcc, 0, v19, vcc
	v_lshl_add_u64 v[26:27], v[26:27], 0, v[168:169]
	v_lshl_add_u64 v[24:25], s[76:77], 0, v[24:25]
	v_add_co_u32_e32 v26, vcc, 0x1000, v26
	v_lshl_add_u64 v[24:25], v[24:25], 0, s[2:3]
	s_nop 0
	v_addc_co_u32_e32 v27, vcc, 0, v27, vcc
	v_lshl_add_u64 v[24:25], v[24:25], 0, v[168:169]
	v_add_co_u32_e32 v28, vcc, 0x1000, v24
	s_lshl_b32 s2, s86, 16
	s_nop 0
	v_addc_co_u32_e32 v29, vcc, 0, v25, vcc
	v_lshl_add_u64 v[36:37], v[40:41], 0, s[2:3]
	global_load_dwordx4 v[0:3], v[0:1], off
	s_nop 0
	global_load_dwordx4 v[4:7], v[4:5], off
	s_nop 0
	global_load_dwordx4 v[8:11], v[8:9], off
	s_nop 0
	global_load_dwordx4 v[12:15], v[12:13], off
	s_nop 0
	global_load_dwordx4 v[16:19], v[16:17], off
	s_nop 0
	global_load_dwordx4 v[20:23], v[20:21], off
	s_nop 0
	global_load_dwordx4 v[24:27], v[26:27], off
	s_nop 0
	global_load_dwordx4 v[28:31], v[28:29], off
	s_waitcnt lgkmcnt(0)
	s_barrier
	global_load_dwordx4 v[128:131], v[36:37], off
	global_load_dwordx4 v[132:135], v[36:37], off offset:16
	global_load_dwordx4 v[136:139], v[36:37], off offset:32
	global_load_dwordx4 v[140:143], v[36:37], off offset:48
	global_load_dwordx4 v[144:147], v[36:37], off offset:64
	global_load_dwordx4 v[148:151], v[36:37], off offset:80
	global_load_dwordx4 v[152:155], v[36:37], off offset:96
	global_load_dwordx4 v[156:159], v[36:37], off offset:112
	s_waitcnt vmcnt(7)
	v_mov_b32_e32 v32, v128
	v_mov_b32_e32 v33, v129
	v_mov_b32_e32 v34, v130
	v_mov_b32_e32 v35, v131
	v_mov_b32_e32 v38, 0
	v_mov_b32_e32 v39, 0
	s_and_saveexec_b64 s[70:71], s[0:1]
	s_cbranch_execz .LBB0_228
	ds_read_b32 v39, v50
	s_waitcnt lgkmcnt(0)
	v_mul_f32_e32 v39, v32, v39
.LBB0_228:
	s_or_b64 exec, exec, s[70:71]
	s_and_saveexec_b64 s[70:71], s[4:5]
	s_cbranch_execz .LBB0_230
	s_nop 0
	ds_read_b32 v32, v50 offset:4
	s_waitcnt lgkmcnt(0)
	v_mul_f32_e32 v38, v33, v32
.LBB0_230:
	s_or_b64 exec, exec, s[70:71]
	s_nop 0
	v_mov_b32_e32 v32, 0
	v_mov_b32_e32 v33, 0
	s_and_saveexec_b64 s[70:71], s[6:7]
	s_cbranch_execz .LBB0_232
	ds_read_b32 v33, v51
	s_waitcnt lgkmcnt(0)
	v_mul_f32_e32 v33, v34, v33

; #define LAS __attribute__((address_space(3)))
; __device__ __forceinline__ unsigned cvt_pk_bf16(float lo, float hi) { unsigned r; asm volatile("v_cvt_pk_bf16_f32 %0, %1, %2" : "=v"(r) : "v"(lo), "v"(hi)); return r; }
; __device__ __forceinline__ void sgu_phase(const Params& p, LAS unsigned char* lds) {
;     ...
;             for (int i = 0; i < 8; ++i) {
;                 const f32x4 wv = *(const f32x4*)(wrow + 4 * i);
;                 float e[4];
; #pragma unroll
;                 for (int q = 0; q < 4; ++q) { const int s = s0 + 4 * i + q; e[q] = (s <= t) ? wv[q] * rsL[s] : 0.f; }
;                 u32x2 pk; pk.x = cvt_pk_bf16(e[0], e[1]); pk.y = cvt_pk_bf16(e[2], e[3]);
;                 *(LAS u32x2*)(WsL + t * 136 + s0 + 4 * i) = pk;
.LBB0_234:
	s_or_b64 exec, exec, s[70:71]
	v_cvt_pk_bf16_f32 v34, v39, v38
	v_cvt_pk_bf16_f32 v35, v33, v32
	ds_write_b64 v114, v[34:35]
	s_waitcnt vmcnt(6)
	v_mov_b32_e32 v32, v132
	v_mov_b32_e32 v33, v133
	v_mov_b32_e32 v34, v134
	v_mov_b32_e32 v35, v135
	v_mov_b32_e32 v38, 0
	v_mov_b32_e32 v39, 0
	s_and_saveexec_b64 s[70:71], s[10:11]
	s_cbranch_execz .LBB0_236
	ds_read_b32 v39, v53
	s_waitcnt lgkmcnt(0)
	v_mul_f32_e32 v39, v32, v39
.LBB0_236:
	s_or_b64 exec, exec, s[70:71]
	s_and_saveexec_b64 s[70:71], s[12:13]
	s_cbranch_execz .LBB0_238
	s_nop 0
	ds_read_b32 v32, v54
	s_waitcnt lgkmcnt(0)
	v_mul_f32_e32 v38, v33, v32
.LBB0_238:
	s_or_b64 exec, exec, s[70:71]
	s_nop 0
	v_mov_b32_e32 v32, 0
	v_mov_b32_e32 v33, 0
	s_and_saveexec_b64 s[70:71], s[14:15]
	s_cbranch_execz .LBB0_240
	ds_read_b32 v33, v55
	s_waitcnt lgkmcnt(0)
	v_mul_f32_e32 v33, v34, v33

; #define LAS __attribute__((address_space(3)))
; __device__ __forceinline__ unsigned cvt_pk_bf16(float lo, float hi) { unsigned r; asm volatile("v_cvt_pk_bf16_f32 %0, %1, %2" : "=v"(r) : "v"(lo), "v"(hi)); return r; }
; __device__ __forceinline__ void sgu_phase(const Params& p, LAS unsigned char* lds) {
;     ...
;             for (int i = 0; i < 8; ++i) {
;                 const f32x4 wv = *(const f32x4*)(wrow + 4 * i);
;                 float e[4];
; #pragma unroll
;                 for (int q = 0; q < 4; ++q) { const int s = s0 + 4 * i + q; e[q] = (s <= t) ? wv[q] * rsL[s] : 0.f; }
;                 u32x2 pk; pk.x = cvt_pk_bf16(e[0], e[1]); pk.y = cvt_pk_bf16(e[2], e[3]);
;                 *(LAS u32x2*)(WsL + t * 136 + s0 + 4 * i) = pk;
.LBB0_242:
	s_or_b64 exec, exec, s[70:71]
	v_cvt_pk_bf16_f32 v34, v39, v38
	v_cvt_pk_bf16_f32 v35, v33, v32
	ds_write_b64 v114, v[34:35] offset:8
	s_waitcnt vmcnt(5)
	v_mov_b32_e32 v32, v136
	v_mov_b32_e32 v33, v137
	v_mov_b32_e32 v34, v138
	v_mov_b32_e32 v35, v139
	v_mov_b32_e32 v38, 0
	v_mov_b32_e32 v39, 0
	s_and_saveexec_b64 s[70:71], s[18:19]
	s_cbranch_execz .LBB0_244
	ds_read_b32 v39, v57
	s_waitcnt lgkmcnt(0)
	v_mul_f32_e32 v39, v32, v39
.LBB0_244:
	s_or_b64 exec, exec, s[70:71]
	s_and_saveexec_b64 s[70:71], s[20:21]
	s_cbranch_execz .LBB0_246
	s_nop 0
	ds_read_b32 v32, v58
	s_waitcnt lgkmcnt(0)
	v_mul_f32_e32 v38, v33, v32
.LBB0_246:
	s_or_b64 exec, exec, s[70:71]
	s_nop 0
	v_mov_b32_e32 v32, 0
	v_mov_b32_e32 v33, 0
	s_and_saveexec_b64 s[70:71], s[22:23]
	s_cbranch_execz .LBB0_248
	ds_read_b32 v33, v59
	s_waitcnt lgkmcnt(0)
	v_mul_f32_e32 v33, v34, v33

; #define LAS __attribute__((address_space(3)))
; __device__ __forceinline__ unsigned cvt_pk_bf16(float lo, float hi) { unsigned r; asm volatile("v_cvt_pk_bf16_f32 %0, %1, %2" : "=v"(r) : "v"(lo), "v"(hi)); return r; }
; __device__ __forceinline__ void sgu_phase(const Params& p, LAS unsigned char* lds) {
;     ...
;             for (int i = 0; i < 8; ++i) {
;                 const f32x4 wv = *(const f32x4*)(wrow + 4 * i);
;                 float e[4];
; #pragma unroll
;                 for (int q = 0; q < 4; ++q) { const int s = s0 + 4 * i + q; e[q] = (s <= t) ? wv[q] * rsL[s] : 0.f; }
;                 u32x2 pk; pk.x = cvt_pk_bf16(e[0], e[1]); pk.y = cvt_pk_bf16(e[2], e[3]);
;                 *(LAS u32x2*)(WsL + t * 136 + s0 + 4 * i) = pk;
.LBB0_250:
	s_or_b64 exec, exec, s[70:71]
	v_cvt_pk_bf16_f32 v34, v39, v38
	v_cvt_pk_bf16_f32 v35, v33, v32
	ds_write_b64 v114, v[34:35] offset:16
	s_waitcnt vmcnt(4)
	v_mov_b32_e32 v32, v140
	v_mov_b32_e32 v33, v141
	v_mov_b32_e32 v34, v142
	v_mov_b32_e32 v35, v143
	v_mov_b32_e32 v38, 0
	v_mov_b32_e32 v39, 0
	s_and_saveexec_b64 s[70:71], s[26:27]
	s_cbranch_execz .LBB0_252
	ds_read_b32 v39, v61
	s_waitcnt lgkmcnt(0)
	v_mul_f32_e32 v39, v32, v39
.LBB0_252:
	s_or_b64 exec, exec, s[70:71]
	s_and_saveexec_b64 s[70:71], s[28:29]
	s_cbranch_execz .LBB0_254
	s_nop 0
	ds_read_b32 v32, v62
	s_waitcnt lgkmcnt(0)
	v_mul_f32_e32 v38, v33, v32
.LBB0_254:
	s_or_b64 exec, exec, s[70:71]
	s_nop 0
	v_mov_b32_e32 v32, 0
	v_mov_b32_e32 v33, 0
	s_and_saveexec_b64 s[70:71], s[30:31]
	s_cbranch_execz .LBB0_256
	ds_read_b32 v33, v63
	s_waitcnt lgkmcnt(0)
	v_mul_f32_e32 v33, v34, v33

; #define LAS __attribute__((address_space(3)))
; __device__ __forceinline__ unsigned cvt_pk_bf16(float lo, float hi) { unsigned r; asm volatile("v_cvt_pk_bf16_f32 %0, %1, %2" : "=v"(r) : "v"(lo), "v"(hi)); return r; }
; __device__ __forceinline__ void sgu_phase(const Params& p, LAS unsigned char* lds) {
;     ...
;             for (int i = 0; i < 8; ++i) {
;                 const f32x4 wv = *(const f32x4*)(wrow + 4 * i);
;                 float e[4];
; #pragma unroll
;                 for (int q = 0; q < 4; ++q) { const int s = s0 + 4 * i + q; e[q] = (s <= t) ? wv[q] * rsL[s] : 0.f; }
;                 u32x2 pk; pk.x = cvt_pk_bf16(e[0], e[1]); pk.y = cvt_pk_bf16(e[2], e[3]);
;                 *(LAS u32x2*)(WsL + t * 136 + s0 + 4 * i) = pk;
.LBB0_258:
	s_or_b64 exec, exec, s[70:71]
	v_cvt_pk_bf16_f32 v34, v39, v38
	v_cvt_pk_bf16_f32 v35, v33, v32
	ds_write_b64 v114, v[34:35] offset:24
	s_waitcnt vmcnt(3)
	v_mov_b32_e32 v32, v144
	v_mov_b32_e32 v33, v145
	v_mov_b32_e32 v34, v146
	v_mov_b32_e32 v35, v147
	v_mov_b32_e32 v38, 0
	v_mov_b32_e32 v39, 0
	s_and_saveexec_b64 s[70:71], s[36:37]
	s_cbranch_execz .LBB0_260
	ds_read_b32 v39, v65
	s_waitcnt lgkmcnt(0)
	v_mul_f32_e32 v39, v32, v39
.LBB0_260:
	s_or_b64 exec, exec, s[70:71]
	s_and_saveexec_b64 s[70:71], s[38:39]
	s_cbranch_execz .LBB0_262
	s_nop 0
	ds_read_b32 v32, v66
	s_waitcnt lgkmcnt(0)
	v_mul_f32_e32 v38, v33, v32
.LBB0_262:
	s_or_b64 exec, exec, s[70:71]
	s_nop 0
	v_mov_b32_e32 v32, 0
	v_mov_b32_e32 v33, 0
	s_and_saveexec_b64 s[70:71], s[40:41]
	s_cbranch_execz .LBB0_264
	ds_read_b32 v33, v67
	s_waitcnt lgkmcnt(0)
	v_mul_f32_e32 v33, v34, v33

; #define LAS __attribute__((address_space(3)))
; __device__ __forceinline__ unsigned cvt_pk_bf16(float lo, float hi) { unsigned r; asm volatile("v_cvt_pk_bf16_f32 %0, %1, %2" : "=v"(r) : "v"(lo), "v"(hi)); return r; }
; __device__ __forceinline__ void sgu_phase(const Params& p, LAS unsigned char* lds) {
;     ...
;             for (int i = 0; i < 8; ++i) {
;                 const f32x4 wv = *(const f32x4*)(wrow + 4 * i);
;                 float e[4];
; #pragma unroll
;                 for (int q = 0; q < 4; ++q) { const int s = s0 + 4 * i + q; e[q] = (s <= t) ? wv[q] * rsL[s] : 0.f; }
;                 u32x2 pk; pk.x = cvt_pk_bf16(e[0], e[1]); pk.y = cvt_pk_bf16(e[2], e[3]);
;                 *(LAS u32x2*)(WsL + t * 136 + s0 + 4 * i) = pk;
.LBB0_266:
	s_or_b64 exec, exec, s[70:71]
	v_cvt_pk_bf16_f32 v34, v39, v38
	v_cvt_pk_bf16_f32 v35, v33, v32
	ds_write_b64 v114, v[34:35] offset:32
	s_waitcnt vmcnt(2)
	v_mov_b32_e32 v32, v148
	v_mov_b32_e32 v33, v149
	v_mov_b32_e32 v34, v150
	v_mov_b32_e32 v35, v151
	v_mov_b32_e32 v38, 0
	v_mov_b32_e32 v39, 0
	s_and_saveexec_b64 s[70:71], s[44:45]
	s_cbranch_execz .LBB0_268
	ds_read_b32 v39, v69
	s_waitcnt lgkmcnt(0)
	v_mul_f32_e32 v39, v32, v39
.LBB0_268:
	s_or_b64 exec, exec, s[70:71]
	s_and_saveexec_b64 s[70:71], s[46:47]
	s_cbranch_execz .LBB0_270
	s_nop 0
	ds_read_b32 v32, v70
	s_waitcnt lgkmcnt(0)
	v_mul_f32_e32 v38, v33, v32
.LBB0_270:
	s_or_b64 exec, exec, s[70:71]
	s_nop 0
	v_mov_b32_e32 v32, 0
	v_mov_b32_e32 v33, 0
	s_and_saveexec_b64 s[70:71], s[48:49]
	s_cbranch_execz .LBB0_272
	ds_read_b32 v33, v71
	s_waitcnt lgkmcnt(0)
	v_mul_f32_e32 v33, v34, v33

; #define LAS __attribute__((address_space(3)))
; __device__ __forceinline__ unsigned cvt_pk_bf16(float lo, float hi) { unsigned r; asm volatile("v_cvt_pk_bf16_f32 %0, %1, %2" : "=v"(r) : "v"(lo), "v"(hi)); return r; }
; __device__ __forceinline__ void sgu_phase(const Params& p, LAS unsigned char* lds) {
;     ...
;             for (int i = 0; i < 8; ++i) {
;                 const f32x4 wv = *(const f32x4*)(wrow + 4 * i);
;                 float e[4];
; #pragma unroll
;                 for (int q = 0; q < 4; ++q) { const int s = s0 + 4 * i + q; e[q] = (s <= t) ? wv[q] * rsL[s] : 0.f; }
;                 u32x2 pk; pk.x = cvt_pk_bf16(e[0], e[1]); pk.y = cvt_pk_bf16(e[2], e[3]);
;                 *(LAS u32x2*)(WsL + t * 136 + s0 + 4 * i) = pk;
.LBB0_274:
	s_or_b64 exec, exec, s[70:71]
	v_cvt_pk_bf16_f32 v34, v39, v38
	v_cvt_pk_bf16_f32 v35, v33, v32
	ds_write_b64 v114, v[34:35] offset:40
	s_waitcnt vmcnt(1)
	v_mov_b32_e32 v32, v152
	v_mov_b32_e32 v33, v153
	v_mov_b32_e32 v34, v154
	v_mov_b32_e32 v35, v155
	v_mov_b32_e32 v38, 0
	v_mov_b32_e32 v39, 0
	s_and_saveexec_b64 s[70:71], s[52:53]
	s_cbranch_execz .LBB0_276
	ds_read_b32 v39, v73
	s_waitcnt lgkmcnt(0)
	v_mul_f32_e32 v39, v32, v39
.LBB0_276:
	s_or_b64 exec, exec, s[70:71]
	s_and_saveexec_b64 s[70:71], s[54:55]
	s_cbranch_execz .LBB0_278
	s_nop 0
	ds_read_b32 v32, v74
	s_waitcnt lgkmcnt(0)
	v_mul_f32_e32 v38, v33, v32
.LBB0_278:
	s_or_b64 exec, exec, s[70:71]
	s_nop 0
	v_mov_b32_e32 v32, 0
	v_mov_b32_e32 v33, 0
	s_and_saveexec_b64 s[70:71], s[56:57]
	s_cbranch_execz .LBB0_280
	ds_read_b32 v33, v75
	s_waitcnt lgkmcnt(0)
	v_mul_f32_e32 v33, v34, v33

; #define LAS __attribute__((address_space(3)))
; __device__ __forceinline__ unsigned cvt_pk_bf16(float lo, float hi) { unsigned r; asm volatile("v_cvt_pk_bf16_f32 %0, %1, %2" : "=v"(r) : "v"(lo), "v"(hi)); return r; }
; __device__ __forceinline__ void sgu_phase(const Params& p, LAS unsigned char* lds) {
;     ...
;             for (int i = 0; i < 8; ++i) {
;                 const f32x4 wv = *(const f32x4*)(wrow + 4 * i);
;                 float e[4];
; #pragma unroll
;                 for (int q = 0; q < 4; ++q) { const int s = s0 + 4 * i + q; e[q] = (s <= t) ? wv[q] * rsL[s] : 0.f; }
;                 u32x2 pk; pk.x = cvt_pk_bf16(e[0], e[1]); pk.y = cvt_pk_bf16(e[2], e[3]);
;                 *(LAS u32x2*)(WsL + t * 136 + s0 + 4 * i) = pk;
.LBB0_282:
	s_or_b64 exec, exec, s[70:71]
	v_cvt_pk_bf16_f32 v34, v39, v38
	v_cvt_pk_bf16_f32 v35, v33, v32
	ds_write_b64 v114, v[34:35] offset:48
	s_waitcnt vmcnt(0)
	v_mov_b32_e32 v32, v156
	v_mov_b32_e32 v33, v157
	v_mov_b32_e32 v34, v158
	v_mov_b32_e32 v35, v159
	v_mov_b32_e32 v36, 0
	v_mov_b32_e32 v37, 0
	s_and_saveexec_b64 s[70:71], s[60:61]
	s_cbranch_execz .LBB0_284
	ds_read_b32 v37, v77
	s_waitcnt lgkmcnt(0)
	v_mul_f32_e32 v37, v32, v37
.LBB0_284:
	s_or_b64 exec, exec, s[70:71]
	s_and_saveexec_b64 s[70:71], s[62:63]
	s_cbranch_execz .LBB0_286
	s_nop 0
	ds_read_b32 v32, v78
	s_waitcnt lgkmcnt(0)
	v_mul_f32_e32 v36, v33, v32
.LBB0_286:
	s_or_b64 exec, exec, s[70:71]
	s_nop 0
	v_mov_b32_e32 v32, 0
	v_mov_b32_e32 v33, 0
	s_and_saveexec_b64 s[70:71], s[64:65]
	s_cbranch_execz .LBB0_288
	ds_read_b32 v33, v79
	s_waitcnt lgkmcnt(0)
	v_mul_f32_e32 v33, v34, v33

;     __device__ __forceinline__ void operator()(const f32x4 (&acc)[2][2][4][2], const Unit& u, int wr, int wc, int fr, int fq) const {
;     ...
;                     f32x4 v0 = acc[ai][bj][m][0] * rs, v1 = acc[ai][bj][m][1] * rs;
;                     if (act == ACT_GELU_VSS) {
;                         f32x2 a = gelu_pk((f32x2){v0[0], v0[1]}), b = gelu_pk((f32x2){v0[2], v0[3]}), c = gelu_pk((f32x2){v1[0], v1[1]}), d = gelu_pk((f32x2){v1[2], v1[3]});
;                         v0 = (f32x4){a.x, a.y, b.x, b.y}; v1 = (f32x4){c.x, c.y, d.x, d.y};
;                         ss += (v0[0] * v0[0] + v0[1] * v0[1]) + (v0[2] * v0[2] + v0[3] * v0[3]) + (v1[0] * v1[0] + v1[1] * v1[1]) + (v1[2] * v1[2] + v1[3] * v1[3]);
;                     } else if (act == ACT_RELU2) {
; #pragma unroll
;                         for (int j = 0; j < 4; ++j) { const float a = fmaxf(v0[j], 0.f), b = fmaxf(v1[j], 0.f); v0[j] = a * a; v1[j] = b * b; }
.LBB0_440:
	s_andn2_b64 vcc, exec, s[0:1]
	s_cbranch_vccnz .LBB0_442
	v_max_f32_e32 v132, 0, v124
	v_max_f32_e32 v138, 0, v120
	v_max_f32_e32 v133, 0, v125
	v_max_f32_e32 v139, 0, v121
	v_max_f32_e32 v140, 0, v126
	v_max_f32_e32 v142, 0, v122
	v_max_f32_e32 v141, 0, v127
	v_max_f32_e32 v129, v123, v123
	v_max_f32_e32 v143, 0, v129
	v_pk_mul_f32 v[134:135], v[132:133], v[132:133]
	v_pk_mul_f32 v[132:133], v[140:141], v[140:141]
	v_pk_mul_f32 v[140:141], v[138:139], v[138:139]
	v_pk_mul_f32 v[138:139], v[142:143], v[142:143]

;     __device__ __forceinline__ void operator()(const f32x4 (&acc)[2][2][4][2], const Unit& u, int wr, int wc, int fr, int fq) const {
;     ...
;                     f32x4 v0 = acc[ai][bj][m][0] * rs, v1 = acc[ai][bj][m][1] * rs;
;                     if (act == ACT_GELU_VSS) {
;                         f32x2 a = gelu_pk((f32x2){v0[0], v0[1]}), b = gelu_pk((f32x2){v0[2], v0[3]}), c = gelu_pk((f32x2){v1[0], v1[1]}), d = gelu_pk((f32x2){v1[2], v1[3]});
;                         v0 = (f32x4){a.x, a.y, b.x, b.y}; v1 = (f32x4){c.x, c.y, d.x, d.y};
;                         ss += (v0[0] * v0[0] + v0[1] * v0[1]) + (v0[2] * v0[2] + v0[3] * v0[3]) + (v1[0] * v1[0] + v1[1] * v1[1]) + (v1[2] * v1[2] + v1[3] * v1[3]);
;                     } else if (act == ACT_RELU2) {
; #pragma unroll
;                         for (int j = 0; j < 4; ++j) { const float a = fmaxf(v0[j], 0.f), b = fmaxf(v1[j], 0.f); v0[j] = a * a; v1[j] = b * b; }
.LBB0_450:
	s_andn2_b64 vcc, exec, s[0:1]
	s_cbranch_vccnz .LBB0_452
	v_max_f32_e32 v127, 0, v113
	v_max_f32_e32 v132, 0, v118
	v_max_f32_e32 v134, 0, v114
	v_max_f32_e32 v126, 0, v112
	v_max_f32_e32 v133, 0, v119
	v_max_f32_e32 v122, 0, v116
	v_max_f32_e32 v123, 0, v117
	v_max_f32_e32 v135, 0, v115
	v_pk_mul_f32 v[124:125], v[122:123], v[122:123]
	v_pk_mul_f32 v[122:123], v[132:133], v[132:133]
	v_pk_mul_f32 v[132:133], v[126:127], v[126:127]
	v_pk_mul_f32 v[126:127], v[134:135], v[134:135]

;     __device__ __forceinline__ void operator()(const f32x4 (&acc)[2][2][4][2], const Unit& u, int wr, int wc, int fr, int fq) const {
;     ...
;                     f32x4 v0 = acc[ai][bj][m][0] * rs, v1 = acc[ai][bj][m][1] * rs;
;                     if (act == ACT_GELU_VSS) {
;                         f32x2 a = gelu_pk((f32x2){v0[0], v0[1]}), b = gelu_pk((f32x2){v0[2], v0[3]}), c = gelu_pk((f32x2){v1[0], v1[1]}), d = gelu_pk((f32x2){v1[2], v1[3]});
;                         v0 = (f32x4){a.x, a.y, b.x, b.y}; v1 = (f32x4){c.x, c.y, d.x, d.y};
;                         ss += (v0[0] * v0[0] + v0[1] * v0[1]) + (v0[2] * v0[2] + v0[3] * v0[3]) + (v1[0] * v1[0] + v1[1] * v1[1]) + (v1[2] * v1[2] + v1[3] * v1[3]);
;                     } else if (act == ACT_RELU2) {
; #pragma unroll
;                         for (int j = 0; j < 4; ++j) { const float a = fmaxf(v0[j], 0.f), b = fmaxf(v1[j], 0.f); v0[j] = a * a; v1[j] = b * b; }
.LBB0_464:
	s_andn2_b64 vcc, exec, s[38:39]
	s_cbranch_vccnz .LBB0_466
	v_max_f32_e32 v117, 0, v105
	v_max_f32_e32 v118, 0, v110
	s_waitcnt lgkmcnt(0)
	v_max_f32_e32 v120, 0, v106
	v_max_f32_e32 v116, 0, v104
	v_max_f32_e32 v119, 0, v111
	v_max_f32_e32 v112, 0, v108
	v_max_f32_e32 v113, 0, v109
	v_max_f32_e32 v121, 0, v107
	v_pk_mul_f32 v[114:115], v[112:113], v[112:113]
	v_pk_mul_f32 v[112:113], v[118:119], v[118:119]
	v_pk_mul_f32 v[118:119], v[116:117], v[116:117]
	v_pk_mul_f32 v[116:117], v[120:121], v[120:121]

;     __device__ __forceinline__ void operator()(const f32x4 (&acc)[2][2][4][2], const Unit& u, int wr, int wc, int fr, int fq) const {
;     ...
;                     f32x4 v0 = acc[ai][bj][m][0] * rs, v1 = acc[ai][bj][m][1] * rs;
;                     if (act == ACT_GELU_VSS) {
;                         f32x2 a = gelu_pk((f32x2){v0[0], v0[1]}), b = gelu_pk((f32x2){v0[2], v0[3]}), c = gelu_pk((f32x2){v1[0], v1[1]}), d = gelu_pk((f32x2){v1[2], v1[3]});
;                         v0 = (f32x4){a.x, a.y, b.x, b.y}; v1 = (f32x4){c.x, c.y, d.x, d.y};
;                         ss += (v0[0] * v0[0] + v0[1] * v0[1]) + (v0[2] * v0[2] + v0[3] * v0[3]) + (v1[0] * v1[0] + v1[1] * v1[1]) + (v1[2] * v1[2] + v1[3] * v1[3]);
;                     } else if (act == ACT_RELU2) {
; #pragma unroll
;                         for (int j = 0; j < 4; ++j) { const float a = fmaxf(v0[j], 0.f), b = fmaxf(v1[j], 0.f); v0[j] = a * a; v1[j] = b * b; }
.LBB0_474:
	s_andn2_b64 vcc, exec, s[38:39]
	s_cbranch_vccnz .LBB0_476
	v_max_f32_e32 v111, 0, v97
	v_max_f32_e32 v112, 0, v102
	v_max_f32_e32 v114, 0, v98
	v_max_f32_e32 v110, 0, v96
	v_max_f32_e32 v113, 0, v103
	v_max_f32_e32 v106, 0, v100
	v_max_f32_e32 v107, 0, v101
	v_max_f32_e32 v115, 0, v99
	v_pk_mul_f32 v[108:109], v[106:107], v[106:107]
	v_pk_mul_f32 v[106:107], v[112:113], v[112:113]
	v_pk_mul_f32 v[112:113], v[110:111], v[110:111]
	v_pk_mul_f32 v[110:111], v[114:115], v[114:115]

;     __device__ __forceinline__ void operator()(const f32x4 (&acc)[2][2][4][2], const Unit& u, int wr, int wc, int fr, int fq) const {
;     ...
;                     f32x4 v0 = acc[ai][bj][m][0] * rs, v1 = acc[ai][bj][m][1] * rs;
;                     if (act == ACT_GELU_VSS) {
;                         f32x2 a = gelu_pk((f32x2){v0[0], v0[1]}), b = gelu_pk((f32x2){v0[2], v0[3]}), c = gelu_pk((f32x2){v1[0], v1[1]}), d = gelu_pk((f32x2){v1[2], v1[3]});
;                         v0 = (f32x4){a.x, a.y, b.x, b.y}; v1 = (f32x4){c.x, c.y, d.x, d.y};
;                         ss += (v0[0] * v0[0] + v0[1] * v0[1]) + (v0[2] * v0[2] + v0[3] * v0[3]) + (v1[0] * v1[0] + v1[1] * v1[1]) + (v1[2] * v1[2] + v1[3] * v1[3]);
;                     } else if (act == ACT_RELU2) {
; #pragma unroll
;                         for (int j = 0; j < 4; ++j) { const float a = fmaxf(v0[j], 0.f), b = fmaxf(v1[j], 0.f); v0[j] = a * a; v1[j] = b * b; }
.LBB0_488:
	s_andn2_b64 vcc, exec, s[38:39]
	s_cbranch_vccnz .LBB0_490
	v_max_f32_e32 v101, 0, v89
	v_max_f32_e32 v102, 0, v94
	s_waitcnt lgkmcnt(0)
	v_max_f32_e32 v104, 0, v90
	v_max_f32_e32 v100, 0, v88
	v_max_f32_e32 v103, 0, v95
	v_max_f32_e32 v96, 0, v92
	v_max_f32_e32 v97, 0, v93
	v_max_f32_e32 v105, 0, v91
	v_pk_mul_f32 v[98:99], v[96:97], v[96:97]
	v_pk_mul_f32 v[96:97], v[102:103], v[102:103]
	v_pk_mul_f32 v[102:103], v[100:101], v[100:101]
	v_pk_mul_f32 v[100:101], v[104:105], v[104:105]

;     __device__ __forceinline__ void operator()(const f32x4 (&acc)[2][2][4][2], const Unit& u, int wr, int wc, int fr, int fq) const {
;     ...
;                     f32x4 v0 = acc[ai][bj][m][0] * rs, v1 = acc[ai][bj][m][1] * rs;
;                     if (act == ACT_GELU_VSS) {
;                         f32x2 a = gelu_pk((f32x2){v0[0], v0[1]}), b = gelu_pk((f32x2){v0[2], v0[3]}), c = gelu_pk((f32x2){v1[0], v1[1]}), d = gelu_pk((f32x2){v1[2], v1[3]});
;                         v0 = (f32x4){a.x, a.y, b.x, b.y}; v1 = (f32x4){c.x, c.y, d.x, d.y};
;                         ss += (v0[0] * v0[0] + v0[1] * v0[1]) + (v0[2] * v0[2] + v0[3] * v0[3]) + (v1[0] * v1[0] + v1[1] * v1[1]) + (v1[2] * v1[2] + v1[3] * v1[3]);
;                     } else if (act == ACT_RELU2) {
; #pragma unroll
;                         for (int j = 0; j < 4; ++j) { const float a = fmaxf(v0[j], 0.f), b = fmaxf(v1[j], 0.f); v0[j] = a * a; v1[j] = b * b; }
.LBB0_498:
	s_andn2_b64 vcc, exec, s[38:39]
	s_cbranch_vccnz .LBB0_500
	v_max_f32_e32 v95, 0, v81
	v_max_f32_e32 v96, 0, v86
	v_max_f32_e32 v98, 0, v82
	v_max_f32_e32 v94, 0, v80
	v_max_f32_e32 v97, 0, v87
	v_max_f32_e32 v90, 0, v84
	v_max_f32_e32 v91, 0, v85
	v_max_f32_e32 v99, 0, v83
	v_pk_mul_f32 v[92:93], v[90:91], v[90:91]
	v_pk_mul_f32 v[90:91], v[96:97], v[96:97]
	v_pk_mul_f32 v[96:97], v[94:95], v[94:95]
	v_pk_mul_f32 v[94:95], v[98:99], v[98:99]

;     __device__ __forceinline__ void operator()(const f32x4 (&acc)[2][2][4][2], const Unit& u, int wr, int wc, int fr, int fq) const {
;     ...
;                     f32x4 v0 = acc[ai][bj][m][0] * rs, v1 = acc[ai][bj][m][1] * rs;
;                     if (act == ACT_GELU_VSS) {
;                         f32x2 a = gelu_pk((f32x2){v0[0], v0[1]}), b = gelu_pk((f32x2){v0[2], v0[3]}), c = gelu_pk((f32x2){v1[0], v1[1]}), d = gelu_pk((f32x2){v1[2], v1[3]});
;                         v0 = (f32x4){a.x, a.y, b.x, b.y}; v1 = (f32x4){c.x, c.y, d.x, d.y};
;                         ss += (v0[0] * v0[0] + v0[1] * v0[1]) + (v0[2] * v0[2] + v0[3] * v0[3]) + (v1[0] * v1[0] + v1[1] * v1[1]) + (v1[2] * v1[2] + v1[3] * v1[3]);
;                     } else if (act == ACT_RELU2) {
; #pragma unroll
;                         for (int j = 0; j < 4; ++j) { const float a = fmaxf(v0[j], 0.f), b = fmaxf(v1[j], 0.f); v0[j] = a * a; v1[j] = b * b; }
.LBB0_512:
	s_andn2_b64 vcc, exec, s[38:39]
	s_cbranch_vccnz .LBB0_514
	v_max_f32_e32 v85, 0, v73
	v_max_f32_e32 v86, 0, v78
	s_waitcnt lgkmcnt(0)
	v_max_f32_e32 v88, 0, v74
	v_max_f32_e32 v84, 0, v72
	v_max_f32_e32 v87, 0, v79
	v_max_f32_e32 v80, 0, v76
	v_max_f32_e32 v81, 0, v77
	v_max_f32_e32 v89, 0, v75
	v_pk_mul_f32 v[82:83], v[80:81], v[80:81]
	v_pk_mul_f32 v[80:81], v[86:87], v[86:87]
	v_pk_mul_f32 v[86:87], v[84:85], v[84:85]
	v_pk_mul_f32 v[84:85], v[88:89], v[88:89]

;     __device__ __forceinline__ void operator()(const f32x4 (&acc)[2][2][4][2], const Unit& u, int wr, int wc, int fr, int fq) const {
;     ...
;                     f32x4 v0 = acc[ai][bj][m][0] * rs, v1 = acc[ai][bj][m][1] * rs;
;                     if (act == ACT_GELU_VSS) {
;                         f32x2 a = gelu_pk((f32x2){v0[0], v0[1]}), b = gelu_pk((f32x2){v0[2], v0[3]}), c = gelu_pk((f32x2){v1[0], v1[1]}), d = gelu_pk((f32x2){v1[2], v1[3]});
;                         v0 = (f32x4){a.x, a.y, b.x, b.y}; v1 = (f32x4){c.x, c.y, d.x, d.y};
;                         ss += (v0[0] * v0[0] + v0[1] * v0[1]) + (v0[2] * v0[2] + v0[3] * v0[3]) + (v1[0] * v1[0] + v1[1] * v1[1]) + (v1[2] * v1[2] + v1[3] * v1[3]);
;                     } else if (act == ACT_RELU2) {
; #pragma unroll
;                         for (int j = 0; j < 4; ++j) { const float a = fmaxf(v0[j], 0.f), b = fmaxf(v1[j], 0.f); v0[j] = a * a; v1[j] = b * b; }
.LBB0_522:
	s_andn2_b64 vcc, exec, s[38:39]
	s_cbranch_vccnz .LBB0_524
	v_max_f32_e32 v79, 0, v65
	v_max_f32_e32 v80, 0, v70
	v_max_f32_e32 v82, 0, v66
	v_max_f32_e32 v78, 0, v64
	v_max_f32_e32 v81, 0, v71
	v_max_f32_e32 v74, 0, v68
	v_max_f32_e32 v75, 0, v69
	v_max_f32_e32 v83, 0, v67
	v_pk_mul_f32 v[76:77], v[74:75], v[74:75]
	v_pk_mul_f32 v[74:75], v[80:81], v[80:81]
	v_pk_mul_f32 v[80:81], v[78:79], v[78:79]
	v_pk_mul_f32 v[78:79], v[82:83], v[82:83]

;     __device__ __forceinline__ void operator()(const f32x4 (&acc)[2][2][4][2], const Unit& u, int wr, int wc, int fr, int fq) const {
;     ...
;                     f32x4 v0 = acc[ai][bj][m][0] * rs, v1 = acc[ai][bj][m][1] * rs;
;                     if (act == ACT_GELU_VSS) {
;                         f32x2 a = gelu_pk((f32x2){v0[0], v0[1]}), b = gelu_pk((f32x2){v0[2], v0[3]}), c = gelu_pk((f32x2){v1[0], v1[1]}), d = gelu_pk((f32x2){v1[2], v1[3]});
;                         v0 = (f32x4){a.x, a.y, b.x, b.y}; v1 = (f32x4){c.x, c.y, d.x, d.y};
;                         ss += (v0[0] * v0[0] + v0[1] * v0[1]) + (v0[2] * v0[2] + v0[3] * v0[3]) + (v1[0] * v1[0] + v1[1] * v1[1]) + (v1[2] * v1[2] + v1[3] * v1[3]);
;                     } else if (act == ACT_RELU2) {
; #pragma unroll
;                         for (int j = 0; j < 4; ++j) { const float a = fmaxf(v0[j], 0.f), b = fmaxf(v1[j], 0.f); v0[j] = a * a; v1[j] = b * b; }
.LBB0_536:
	s_andn2_b64 vcc, exec, s[38:39]
	s_cbranch_vccnz .LBB0_538
	v_max_f32_e32 v69, 0, v57
	v_max_f32_e32 v70, 0, v62
	s_waitcnt lgkmcnt(0)
	v_max_f32_e32 v72, 0, v58
	v_max_f32_e32 v68, 0, v56
	v_max_f32_e32 v71, 0, v63
	v_max_f32_e32 v64, 0, v60
	v_max_f32_e32 v65, 0, v61
	v_max_f32_e32 v73, 0, v59
	v_pk_mul_f32 v[66:67], v[64:65], v[64:65]
	v_pk_mul_f32 v[64:65], v[70:71], v[70:71]
	v_pk_mul_f32 v[70:71], v[68:69], v[68:69]
	v_pk_mul_f32 v[68:69], v[72:73], v[72:73]

;     __device__ __forceinline__ void operator()(const f32x4 (&acc)[2][2][4][2], const Unit& u, int wr, int wc, int fr, int fq) const {
;     ...
;                     f32x4 v0 = acc[ai][bj][m][0] * rs, v1 = acc[ai][bj][m][1] * rs;
;                     if (act == ACT_GELU_VSS) {
;                         f32x2 a = gelu_pk((f32x2){v0[0], v0[1]}), b = gelu_pk((f32x2){v0[2], v0[3]}), c = gelu_pk((f32x2){v1[0], v1[1]}), d = gelu_pk((f32x2){v1[2], v1[3]});
;                         v0 = (f32x4){a.x, a.y, b.x, b.y}; v1 = (f32x4){c.x, c.y, d.x, d.y};
;                         ss += (v0[0] * v0[0] + v0[1] * v0[1]) + (v0[2] * v0[2] + v0[3] * v0[3]) + (v1[0] * v1[0] + v1[1] * v1[1]) + (v1[2] * v1[2] + v1[3] * v1[3]);
;                     } else if (act == ACT_RELU2) {
; #pragma unroll
;                         for (int j = 0; j < 4; ++j) { const float a = fmaxf(v0[j], 0.f), b = fmaxf(v1[j], 0.f); v0[j] = a * a; v1[j] = b * b; }
.LBB0_546:
	s_andn2_b64 vcc, exec, s[38:39]
	s_cbranch_vccnz .LBB0_548
	v_max_f32_e32 v65, 0, v49
	v_max_f32_e32 v66, 0, v54
	v_max_f32_e32 v68, 0, v50
	v_max_f32_e32 v64, 0, v48
	v_max_f32_e32 v67, 0, v55
	v_max_f32_e32 v60, 0, v52
	v_max_f32_e32 v61, 0, v53
	v_max_f32_e32 v69, 0, v51
	v_pk_mul_f32 v[62:63], v[60:61], v[60:61]
	v_pk_mul_f32 v[60:61], v[66:67], v[66:67]
	v_pk_mul_f32 v[66:67], v[64:65], v[64:65]
	v_pk_mul_f32 v[64:65], v[68:69], v[68:69]

;     __device__ __forceinline__ void operator()(const f32x4 (&acc)[2][2][4][2], const Unit& u, int wr, int wc, int fr, int fq) const {
;     ...
;                     f32x4 v0 = acc[ai][bj][m][0] * rs, v1 = acc[ai][bj][m][1] * rs;
;                     if (act == ACT_GELU_VSS) {
;                         f32x2 a = gelu_pk((f32x2){v0[0], v0[1]}), b = gelu_pk((f32x2){v0[2], v0[3]}), c = gelu_pk((f32x2){v1[0], v1[1]}), d = gelu_pk((f32x2){v1[2], v1[3]});
;                         v0 = (f32x4){a.x, a.y, b.x, b.y}; v1 = (f32x4){c.x, c.y, d.x, d.y};
;                         ss += (v0[0] * v0[0] + v0[1] * v0[1]) + (v0[2] * v0[2] + v0[3] * v0[3]) + (v1[0] * v1[0] + v1[1] * v1[1]) + (v1[2] * v1[2] + v1[3] * v1[3]);
;                     } else if (act == ACT_RELU2) {
; #pragma unroll
;                         for (int j = 0; j < 4; ++j) { const float a = fmaxf(v0[j], 0.f), b = fmaxf(v1[j], 0.f); v0[j] = a * a; v1[j] = b * b; }
.LBB0_560:
	s_andn2_b64 vcc, exec, s[38:39]
	s_cbranch_vccnz .LBB0_562
	v_max_f32_e32 v53, 0, v41
	v_max_f32_e32 v54, 0, v46
	s_waitcnt lgkmcnt(0)
	v_max_f32_e32 v56, 0, v42
	v_max_f32_e32 v52, 0, v40
	v_max_f32_e32 v55, 0, v47
	v_max_f32_e32 v48, 0, v44
	v_max_f32_e32 v49, 0, v45
	v_max_f32_e32 v57, 0, v43
	v_pk_mul_f32 v[50:51], v[48:49], v[48:49]
	v_pk_mul_f32 v[48:49], v[54:55], v[54:55]
	v_pk_mul_f32 v[54:55], v[52:53], v[52:53]
	v_pk_mul_f32 v[52:53], v[56:57], v[56:57]

;     __device__ __forceinline__ void operator()(const f32x4 (&acc)[2][2][4][2], const Unit& u, int wr, int wc, int fr, int fq) const {
;     ...
;                     f32x4 v0 = acc[ai][bj][m][0] * rs, v1 = acc[ai][bj][m][1] * rs;
;                     if (act == ACT_GELU_VSS) {
;                         f32x2 a = gelu_pk((f32x2){v0[0], v0[1]}), b = gelu_pk((f32x2){v0[2], v0[3]}), c = gelu_pk((f32x2){v1[0], v1[1]}), d = gelu_pk((f32x2){v1[2], v1[3]});
;                         v0 = (f32x4){a.x, a.y, b.x, b.y}; v1 = (f32x4){c.x, c.y, d.x, d.y};
;                         ss += (v0[0] * v0[0] + v0[1] * v0[1]) + (v0[2] * v0[2] + v0[3] * v0[3]) + (v1[0] * v1[0] + v1[1] * v1[1]) + (v1[2] * v1[2] + v1[3] * v1[3]);
;                     } else if (act == ACT_RELU2) {
; #pragma unroll
;                         for (int j = 0; j < 4; ++j) { const float a = fmaxf(v0[j], 0.f), b = fmaxf(v1[j], 0.f); v0[j] = a * a; v1[j] = b * b; }
.LBB0_570:
	s_andn2_b64 vcc, exec, s[38:39]
	s_cbranch_vccnz .LBB0_572
	v_max_f32_e32 v49, 0, v33
	v_max_f32_e32 v50, 0, v38
	v_max_f32_e32 v52, 0, v34
	v_max_f32_e32 v48, 0, v32
	v_max_f32_e32 v51, 0, v39
	v_max_f32_e32 v44, 0, v36
	v_max_f32_e32 v45, 0, v37
	v_max_f32_e32 v53, 0, v35
	v_pk_mul_f32 v[46:47], v[44:45], v[44:45]
	v_pk_mul_f32 v[44:45], v[50:51], v[50:51]
	v_pk_mul_f32 v[50:51], v[48:49], v[48:49]
	v_pk_mul_f32 v[48:49], v[52:53], v[52:53]

;     __device__ __forceinline__ void operator()(const f32x4 (&acc)[2][2][4][2], const Unit& u, int wr, int wc, int fr, int fq) const {
;     ...
;                     f32x4 v0 = acc[ai][bj][m][0] * rs, v1 = acc[ai][bj][m][1] * rs;
;                     if (act == ACT_GELU_VSS) {
;                         f32x2 a = gelu_pk((f32x2){v0[0], v0[1]}), b = gelu_pk((f32x2){v0[2], v0[3]}), c = gelu_pk((f32x2){v1[0], v1[1]}), d = gelu_pk((f32x2){v1[2], v1[3]});
;                         v0 = (f32x4){a.x, a.y, b.x, b.y}; v1 = (f32x4){c.x, c.y, d.x, d.y};
;                         ss += (v0[0] * v0[0] + v0[1] * v0[1]) + (v0[2] * v0[2] + v0[3] * v0[3]) + (v1[0] * v1[0] + v1[1] * v1[1]) + (v1[2] * v1[2] + v1[3] * v1[3]);
;                     } else if (act == ACT_RELU2) {
; #pragma unroll
;                         for (int j = 0; j < 4; ++j) { const float a = fmaxf(v0[j], 0.f), b = fmaxf(v1[j], 0.f); v0[j] = a * a; v1[j] = b * b; }
.LBB0_584:
	s_andn2_b64 vcc, exec, s[38:39]
	s_cbranch_vccnz .LBB0_586
	v_max_f32_e32 v37, 0, v25
	v_max_f32_e32 v38, 0, v30
	s_waitcnt lgkmcnt(0)
	v_max_f32_e32 v40, 0, v26
	v_max_f32_e32 v36, 0, v24
	v_max_f32_e32 v39, 0, v31
	v_max_f32_e32 v32, 0, v28
	v_max_f32_e32 v33, 0, v29
	v_max_f32_e32 v41, 0, v27
	v_pk_mul_f32 v[34:35], v[32:33], v[32:33]
	v_pk_mul_f32 v[32:33], v[38:39], v[38:39]
	v_pk_mul_f32 v[38:39], v[36:37], v[36:37]
	v_pk_mul_f32 v[36:37], v[40:41], v[40:41]

;     __device__ __forceinline__ void operator()(const f32x4 (&acc)[2][2][4][2], const Unit& u, int wr, int wc, int fr, int fq) const {
;     ...
;                     f32x4 v0 = acc[ai][bj][m][0] * rs, v1 = acc[ai][bj][m][1] * rs;
;                     if (act == ACT_GELU_VSS) {
;                         f32x2 a = gelu_pk((f32x2){v0[0], v0[1]}), b = gelu_pk((f32x2){v0[2], v0[3]}), c = gelu_pk((f32x2){v1[0], v1[1]}), d = gelu_pk((f32x2){v1[2], v1[3]});
;                         v0 = (f32x4){a.x, a.y, b.x, b.y}; v1 = (f32x4){c.x, c.y, d.x, d.y};
;                         ss += (v0[0] * v0[0] + v0[1] * v0[1]) + (v0[2] * v0[2] + v0[3] * v0[3]) + (v1[0] * v1[0] + v1[1] * v1[1]) + (v1[2] * v1[2] + v1[3] * v1[3]);
;                     } else if (act == ACT_RELU2) {
; #pragma unroll
;                         for (int j = 0; j < 4; ++j) { const float a = fmaxf(v0[j], 0.f), b = fmaxf(v1[j], 0.f); v0[j] = a * a; v1[j] = b * b; }
.LBB0_594:
	s_andn2_b64 vcc, exec, s[38:39]
	s_cbranch_vccnz .LBB0_596
	v_max_f32_e32 v33, 0, v17
	v_max_f32_e32 v34, 0, v22
	v_max_f32_e32 v36, 0, v18
	v_max_f32_e32 v32, 0, v16
	v_max_f32_e32 v35, 0, v23
	v_max_f32_e32 v28, 0, v20
	v_max_f32_e32 v29, 0, v21
	v_max_f32_e32 v37, 0, v19
	v_pk_mul_f32 v[30:31], v[28:29], v[28:29]
	v_pk_mul_f32 v[28:29], v[34:35], v[34:35]
	v_pk_mul_f32 v[34:35], v[32:33], v[32:33]
	v_pk_mul_f32 v[32:33], v[36:37], v[36:37]

;     __device__ __forceinline__ void operator()(const f32x4 (&acc)[2][2][4][2], const Unit& u, int wr, int wc, int fr, int fq) const {
;     ...
;                     f32x4 v0 = acc[ai][bj][m][0] * rs, v1 = acc[ai][bj][m][1] * rs;
;                     if (act == ACT_GELU_VSS) {
;                         f32x2 a = gelu_pk((f32x2){v0[0], v0[1]}), b = gelu_pk((f32x2){v0[2], v0[3]}), c = gelu_pk((f32x2){v1[0], v1[1]}), d = gelu_pk((f32x2){v1[2], v1[3]});
;                         v0 = (f32x4){a.x, a.y, b.x, b.y}; v1 = (f32x4){c.x, c.y, d.x, d.y};
;                         ss += (v0[0] * v0[0] + v0[1] * v0[1]) + (v0[2] * v0[2] + v0[3] * v0[3]) + (v1[0] * v1[0] + v1[1] * v1[1]) + (v1[2] * v1[2] + v1[3] * v1[3]);
;                     } else if (act == ACT_RELU2) {
; #pragma unroll
;                         for (int j = 0; j < 4; ++j) { const float a = fmaxf(v0[j], 0.f), b = fmaxf(v1[j], 0.f); v0[j] = a * a; v1[j] = b * b; }
.LBB0_608:
	s_andn2_b64 vcc, exec, s[38:39]
	s_cbranch_vccnz .LBB0_610
	v_max_f32_e32 v21, 0, v9
	v_max_f32_e32 v22, 0, v14
	s_waitcnt lgkmcnt(0)
	v_max_f32_e32 v24, 0, v10
	v_max_f32_e32 v20, 0, v8
	v_max_f32_e32 v23, 0, v15
	v_max_f32_e32 v16, 0, v12
	v_max_f32_e32 v17, 0, v13
	v_max_f32_e32 v25, 0, v11
	v_pk_mul_f32 v[18:19], v[16:17], v[16:17]
	v_pk_mul_f32 v[16:17], v[22:23], v[22:23]
	v_pk_mul_f32 v[22:23], v[20:21], v[20:21]
	v_pk_mul_f32 v[20:21], v[24:25], v[24:25]

;     __device__ __forceinline__ void operator()(const f32x4 (&acc)[2][2][4][2], const Unit& u, int wr, int wc, int fr, int fq) const {
;     ...
;                     f32x4 v0 = acc[ai][bj][m][0] * rs, v1 = acc[ai][bj][m][1] * rs;
;                     if (act == ACT_GELU_VSS) {
;                         f32x2 a = gelu_pk((f32x2){v0[0], v0[1]}), b = gelu_pk((f32x2){v0[2], v0[3]}), c = gelu_pk((f32x2){v1[0], v1[1]}), d = gelu_pk((f32x2){v1[2], v1[3]});
;                         v0 = (f32x4){a.x, a.y, b.x, b.y}; v1 = (f32x4){c.x, c.y, d.x, d.y};
;                         ss += (v0[0] * v0[0] + v0[1] * v0[1]) + (v0[2] * v0[2] + v0[3] * v0[3]) + (v1[0] * v1[0] + v1[1] * v1[1]) + (v1[2] * v1[2] + v1[3] * v1[3]);
;                     } else if (act == ACT_RELU2) {
; #pragma unroll
;                         for (int j = 0; j < 4; ++j) { const float a = fmaxf(v0[j], 0.f), b = fmaxf(v1[j], 0.f); v0[j] = a * a; v1[j] = b * b; }
.LBB0_618:
	s_andn2_b64 vcc, exec, s[38:39]
	s_cbranch_vccnz .LBB0_620
	v_max_f32_e32 v17, 0, v1
	v_max_f32_e32 v18, 0, v6
	v_max_f32_e32 v20, 0, v2
	v_max_f32_e32 v16, 0, v0
	v_max_f32_e32 v19, 0, v7
	v_max_f32_e32 v12, 0, v4
	v_max_f32_e32 v13, 0, v5
	v_max_f32_e32 v21, 0, v3
	v_pk_mul_f32 v[14:15], v[12:13], v[12:13]
	v_pk_mul_f32 v[12:13], v[18:19], v[18:19]
	v_pk_mul_f32 v[18:19], v[16:17], v[16:17]
	v_pk_mul_f32 v[16:17], v[20:21], v[20:21]
